# on top of previous: removed the grid barrier between final_phase of half 0 and load_half of half 1 (each row is read then rewritten by the same wave)
# speedup vs baseline: 1.0084x; 1.0084x over previous
; #define LAS __attribute__((address_space(3)))
; template <class T> __device__ __forceinline__ T* opq_ptr(T* p) { asm volatile("" : "+s"(p)); return p; }
; __device__ __forceinline__ int opq_s(int v) { asm volatile("" : "+s"(v)); return v; }
; __device__ __forceinline__ unsigned xb_xcc_id() { return (unsigned)__builtin_amdgcn_s_getreg((3 << 11) | 20) & 0xFu; }
; #define WSP(T, off) ((GAS T*)(opq_ptr(P.ws) + (off)))
; __global__ void __launch_bounds__(512, 2) mega_fwd(Params P) {
;     ...
;         final_phase(WSP(const bf16_t, OFF_XB), GP(float, P.out) + (size_t)hb * TH * D, GP(const float, P.norm_final), opq_s(gridDim.x), opq_s(blockIdx.x));
;         if (hb == 0) { XcdBarrier bar; bar.bar = (unsigned*)opq_ptr(P.ws); bar.x = xb_xcc_id(); bar.st = (volatile LAS unsigned*)(lds + 131072); xcd_barrier(bar); }
;     }
.LBB0_846:
	s_or_b64 exec, exec, s[4:5]
	v_readlane_b32 s4, v254, 43
	v_readlane_b32 s5, v254, 44
	s_mov_b64 s[2:3], -1
	s_and_b64 vcc, exec, s[4:5]
	s_cbranch_vccz .Lskipbar_exit
	s_mov_b64 s[2:3], 0
